# residual GEMM phases (attention out-projection and down-projection): workgroups on XCDs 4-7 start 5 sleep quanta late so their HBM-bound epilogues overlap the other half's K-loops
# baseline (speedup 1.0000x reference)
; __global__ void __launch_bounds__(NWAVES * 64, 2) mk_fwd(Args args) {
;     ...
;             } else if (k == 4 || k == 6) {
;                 pg8::Gemm g{k == 4 ? VAb : ACT, (const bf16*)(wl + (k == 4 ? WO_O : WO_DN)), M, DM, k == 4 ? DM : DFF}; pg8::StaticOrder S; S.init(M / 256, DM / 256, G, bx);
;                 const bool leave = (k == 4) || (l + 1 < DEPTH);
;                 pg8::EpiRes E{(l == 0 && k == 4) ? x_in : xo, xo, leave ? HB : nullptr, k == 4 ? ap->in[16] + l * DM : ap->in[1] + (l + 1 < DEPTH ? l + 1 : l) * DM, rss};
;                 pg8::gemm_phase<pg8::EpiRes, pg8::StaticOrder, true, true>(lds, g, S, E);
.LBB0_31:
	s_bitcmp1_b32 s34, 2
	s_cbranch_scc0 .Lstag_done
	s_mov_b32 s2, 0
	s_cmp_eq_u32 s74, 5
	s_cselect_b32 s2, 5, s2
	s_cmp_eq_u32 s74, 12
	s_cselect_b32 s2, 5, s2
	s_cmp_eq_u32 s74, 7
	s_cselect_b32 s2, 5, s2
	s_cmp_eq_u32 s74, 14
	s_cselect_b32 s2, 5, s2
	s_cmp_eq_u32 s2, 0
	s_cbranch_scc1 .Lstag_done
.Lstag_loop:
	s_sleep 127
	s_add_i32 s2, s2, -1
	s_cmp_lg_u32 s2, 0
	s_cbranch_scc1 .Lstag_loop
